# baseline (speedup 1.0000x reference)
.Lgscan_q0:
	s_add_i32 s34, s34, 4
	s_lshl_b32 s35, s34, 8
	s_and_b32 s18, s34, 15
	s_lshl_b32 s18, s18, 4
	s_or_b32 s35, s35, s18
	v_xor_b32_e32 v132, s35, v131
	ds_read_b32 v230, v132
	v_xor_b32_e32 v243, 0x110, v132
	ds_read_b32 v231, v243
	v_xor_b32_e32 v244, 0x220, v132
	ds_read_b32 v232, v244
	v_xor_b32_e32 v245, 0x330, v132
	ds_read_b32 v233, v245
	s_waitcnt lgkmcnt(4)
	v_cvt_f32_f16_sdwa v234, v226 dst_sel:DWORD dst_unused:UNUSED_PAD src0_sel:WORD_1
	v_cvt_f32_f16_sdwa v235, v227 dst_sel:DWORD dst_unused:UNUSED_PAD src0_sel:WORD_1
	v_cvt_f32_f16_sdwa v236, v228 dst_sel:DWORD dst_unused:UNUSED_PAD src0_sel:WORD_1
	v_cvt_f32_f16_sdwa v237, v229 dst_sel:DWORD dst_unused:UNUSED_PAD src0_sel:WORD_1
	v_cvt_f32_f16_e32 v226, v226
	v_cvt_f32_f16_e32 v227, v227
	v_cvt_f32_f16_e32 v228, v228
	v_cvt_f32_f16_e32 v229, v229
	v_mul_f32_e32 v226, v130, v226
	v_mul_f32_e32 v227, v130, v227
	v_mul_f32_e32 v228, v130, v228
	v_mul_f32_e32 v229, v130, v229
	v_mul_f32_e32 v238, 0x3fb8aa3b, v226
	v_mul_f32_e32 v239, 0x3fb8aa3b, v227
	v_mul_f32_e32 v240, 0x3fb8aa3b, v228
	v_mul_f32_e32 v241, 0x3fb8aa3b, v229
	v_exp_f32_e32 v238, v238
	v_exp_f32_e32 v239, v239
	v_exp_f32_e32 v240, v240
	v_exp_f32_e32 v241, v241
	v_fma_f32 v242, -v238, v238, 1.0
	v_fma_f32 v243, -v239, v239, 1.0
	v_fma_f32 v244, -v240, v240, 1.0
	v_fma_f32 v245, -v241, v241, 1.0
	v_max_f32_e32 v242, 0, v242
	v_max_f32_e32 v243, 0, v243
	v_max_f32_e32 v244, 0, v244
	v_max_f32_e32 v245, 0, v245
	v_sqrt_f32_e32 v242, v242
	v_sqrt_f32_e32 v243, v243
	v_sqrt_f32_e32 v244, v244
	v_sqrt_f32_e32 v245, v245
	v_mul_f32_e32 v234, v242, v234
	v_mul_f32_e32 v235, v243, v235
	v_mul_f32_e32 v236, v244, v236
	v_mul_f32_e32 v237, v245, v237
	v_mul_f32_e32 v129, v129, v238
	v_add_f32_e32 v128, v128, v226
	v_add_f32_e32 v129, v129, v234
	v_mul_f32_e32 v129, v129, v239
	v_add_f32_e32 v128, v128, v227
	v_add_f32_e32 v129, v129, v235
	v_mul_f32_e32 v129, v129, v240
	v_add_f32_e32 v128, v128, v228
	v_add_f32_e32 v129, v129, v236
	v_mul_f32_e32 v129, v129, v241
	v_add_f32_e32 v128, v128, v229
	v_add_f32_e32 v129, v129, v237
	s_add_i32 s34, s34, 4
	s_lshl_b32 s35, s34, 8
	s_and_b32 s18, s34, 15
	s_lshl_b32 s18, s18, 4
	s_or_b32 s35, s35, s18
	v_xor_b32_e32 v132, s35, v131
	ds_read_b32 v226, v132
	v_xor_b32_e32 v243, 0x110, v132
	ds_read_b32 v227, v243
	v_xor_b32_e32 v244, 0x220, v132
	ds_read_b32 v228, v244
	v_xor_b32_e32 v245, 0x330, v132
	ds_read_b32 v229, v245
	s_waitcnt lgkmcnt(4)
	v_cvt_f32_f16_sdwa v234, v230 dst_sel:DWORD dst_unused:UNUSED_PAD src0_sel:WORD_1
	v_cvt_f32_f16_sdwa v235, v231 dst_sel:DWORD dst_unused:UNUSED_PAD src0_sel:WORD_1
	v_cvt_f32_f16_sdwa v236, v232 dst_sel:DWORD dst_unused:UNUSED_PAD src0_sel:WORD_1
	v_cvt_f32_f16_sdwa v237, v233 dst_sel:DWORD dst_unused:UNUSED_PAD src0_sel:WORD_1
	v_cvt_f32_f16_e32 v230, v230
	v_cvt_f32_f16_e32 v231, v231
	v_cvt_f32_f16_e32 v232, v232
	v_cvt_f32_f16_e32 v233, v233
	v_mul_f32_e32 v230, v130, v230
	v_mul_f32_e32 v231, v130, v231
	v_mul_f32_e32 v232, v130, v232
	v_mul_f32_e32 v233, v130, v233
	v_mul_f32_e32 v238, 0x3fb8aa3b, v230
	v_mul_f32_e32 v239, 0x3fb8aa3b, v231
	v_mul_f32_e32 v240, 0x3fb8aa3b, v232
	v_mul_f32_e32 v241, 0x3fb8aa3b, v233
	v_exp_f32_e32 v238, v238
	v_exp_f32_e32 v239, v239
	v_exp_f32_e32 v240, v240
	v_exp_f32_e32 v241, v241
	v_fma_f32 v242, -v238, v238, 1.0
	v_fma_f32 v243, -v239, v239, 1.0
	v_fma_f32 v244, -v240, v240, 1.0
	v_fma_f32 v245, -v241, v241, 1.0
	v_max_f32_e32 v242, 0, v242
	v_max_f32_e32 v243, 0, v243
	v_max_f32_e32 v244, 0, v244
	v_max_f32_e32 v245, 0, v245
	v_sqrt_f32_e32 v242, v242
	v_sqrt_f32_e32 v243, v243
	v_sqrt_f32_e32 v244, v244
	v_sqrt_f32_e32 v245, v245
	v_mul_f32_e32 v234, v242, v234
	v_mul_f32_e32 v235, v243, v235
	v_mul_f32_e32 v236, v244, v236
	v_mul_f32_e32 v237, v245, v237
	v_mul_f32_e32 v129, v129, v238
	v_add_f32_e32 v128, v128, v230
	v_add_f32_e32 v129, v129, v234
	v_mul_f32_e32 v129, v129, v239
	v_add_f32_e32 v128, v128, v231
	v_add_f32_e32 v129, v129, v235
	v_mul_f32_e32 v129, v129, v240
	v_add_f32_e32 v128, v128, v232
	v_add_f32_e32 v129, v129, v236
	v_mul_f32_e32 v129, v129, v241
	v_add_f32_e32 v128, v128, v233
	v_add_f32_e32 v129, v129, v237
	s_cmp_lt_u32 s34, 64
	s_cbranch_scc1 .Lgscan_q0
	s_waitcnt lgkmcnt(0)
	v_mul_f32_e32 v128, 0x3fb8aa3b, v128
	v_exp_f32_e32 v128, v128
	v_or_b32_e32 v130, v138, v136
	v_ashrrev_i32_e32 v131, 31, v130
	v_lshl_add_u64 v[130:131], v[130:131], 2, s[14:15]
	global_store_dword v[130:131], v128, off
	v_or_b32_e32 v130, v141, v136
	v_ashrrev_i32_e32 v131, 31, v130
	v_lshl_add_u64 v[130:131], v[130:131], 2, s[14:15]
	v_mov_b32_e32 v200, v156
	global_store_dword v[130:131], v129, off

.Lgscan_q1:
	s_add_i32 s34, s34, 4
	s_lshl_b32 s35, s34, 8
	s_and_b32 s18, s34, 15
	s_lshl_b32 s18, s18, 4
	s_or_b32 s35, s35, s18
	v_xor_b32_e32 v132, s35, v131
	ds_read_b32 v230, v132
	v_xor_b32_e32 v243, 0x110, v132
	ds_read_b32 v231, v243
	v_xor_b32_e32 v244, 0x220, v132
	ds_read_b32 v232, v244
	v_xor_b32_e32 v245, 0x330, v132
	ds_read_b32 v233, v245
	s_waitcnt lgkmcnt(4)
	v_cvt_f32_f16_sdwa v234, v226 dst_sel:DWORD dst_unused:UNUSED_PAD src0_sel:WORD_1
	v_cvt_f32_f16_sdwa v235, v227 dst_sel:DWORD dst_unused:UNUSED_PAD src0_sel:WORD_1
	v_cvt_f32_f16_sdwa v236, v228 dst_sel:DWORD dst_unused:UNUSED_PAD src0_sel:WORD_1
	v_cvt_f32_f16_sdwa v237, v229 dst_sel:DWORD dst_unused:UNUSED_PAD src0_sel:WORD_1
	v_cvt_f32_f16_e32 v226, v226
	v_cvt_f32_f16_e32 v227, v227
	v_cvt_f32_f16_e32 v228, v228
	v_cvt_f32_f16_e32 v229, v229
	v_mul_f32_e32 v226, v130, v226
	v_mul_f32_e32 v227, v130, v227
	v_mul_f32_e32 v228, v130, v228
	v_mul_f32_e32 v229, v130, v229
	v_mul_f32_e32 v238, 0x3fb8aa3b, v226
	v_mul_f32_e32 v239, 0x3fb8aa3b, v227
	v_mul_f32_e32 v240, 0x3fb8aa3b, v228
	v_mul_f32_e32 v241, 0x3fb8aa3b, v229
	v_exp_f32_e32 v238, v238
	v_exp_f32_e32 v239, v239
	v_exp_f32_e32 v240, v240
	v_exp_f32_e32 v241, v241
	v_fma_f32 v242, -v238, v238, 1.0
	v_fma_f32 v243, -v239, v239, 1.0
	v_fma_f32 v244, -v240, v240, 1.0
	v_fma_f32 v245, -v241, v241, 1.0
	v_max_f32_e32 v242, 0, v242
	v_max_f32_e32 v243, 0, v243
	v_max_f32_e32 v244, 0, v244
	v_max_f32_e32 v245, 0, v245
	v_sqrt_f32_e32 v242, v242
	v_sqrt_f32_e32 v243, v243
	v_sqrt_f32_e32 v244, v244
	v_sqrt_f32_e32 v245, v245
	v_mul_f32_e32 v234, v242, v234
	v_mul_f32_e32 v235, v243, v235
	v_mul_f32_e32 v236, v244, v236
	v_mul_f32_e32 v237, v245, v237
	v_mul_f32_e32 v129, v129, v238
	v_add_f32_e32 v128, v128, v226
	v_add_f32_e32 v129, v129, v234
	v_mul_f32_e32 v129, v129, v239
	v_add_f32_e32 v128, v128, v227
	v_add_f32_e32 v129, v129, v235
	v_mul_f32_e32 v129, v129, v240
	v_add_f32_e32 v128, v128, v228
	v_add_f32_e32 v129, v129, v236
	v_mul_f32_e32 v129, v129, v241
	v_add_f32_e32 v128, v128, v229
	v_add_f32_e32 v129, v129, v237
	s_add_i32 s34, s34, 4
	s_lshl_b32 s35, s34, 8
	s_and_b32 s18, s34, 15
	s_lshl_b32 s18, s18, 4
	s_or_b32 s35, s35, s18
	v_xor_b32_e32 v132, s35, v131
	ds_read_b32 v226, v132
	v_xor_b32_e32 v243, 0x110, v132
	ds_read_b32 v227, v243
	v_xor_b32_e32 v244, 0x220, v132
	ds_read_b32 v228, v244
	v_xor_b32_e32 v245, 0x330, v132
	ds_read_b32 v229, v245
	s_waitcnt lgkmcnt(4)
	v_cvt_f32_f16_sdwa v234, v230 dst_sel:DWORD dst_unused:UNUSED_PAD src0_sel:WORD_1
	v_cvt_f32_f16_sdwa v235, v231 dst_sel:DWORD dst_unused:UNUSED_PAD src0_sel:WORD_1
	v_cvt_f32_f16_sdwa v236, v232 dst_sel:DWORD dst_unused:UNUSED_PAD src0_sel:WORD_1
	v_cvt_f32_f16_sdwa v237, v233 dst_sel:DWORD dst_unused:UNUSED_PAD src0_sel:WORD_1
	v_cvt_f32_f16_e32 v230, v230
	v_cvt_f32_f16_e32 v231, v231
	v_cvt_f32_f16_e32 v232, v232
	v_cvt_f32_f16_e32 v233, v233
	v_mul_f32_e32 v230, v130, v230
	v_mul_f32_e32 v231, v130, v231
	v_mul_f32_e32 v232, v130, v232
	v_mul_f32_e32 v233, v130, v233
	v_mul_f32_e32 v238, 0x3fb8aa3b, v230
	v_mul_f32_e32 v239, 0x3fb8aa3b, v231
	v_mul_f32_e32 v240, 0x3fb8aa3b, v232
	v_mul_f32_e32 v241, 0x3fb8aa3b, v233
	v_exp_f32_e32 v238, v238
	v_exp_f32_e32 v239, v239
	v_exp_f32_e32 v240, v240
	v_exp_f32_e32 v241, v241
	v_fma_f32 v242, -v238, v238, 1.0
	v_fma_f32 v243, -v239, v239, 1.0
	v_fma_f32 v244, -v240, v240, 1.0
	v_fma_f32 v245, -v241, v241, 1.0
	v_max_f32_e32 v242, 0, v242
	v_max_f32_e32 v243, 0, v243
	v_max_f32_e32 v244, 0, v244
	v_max_f32_e32 v245, 0, v245
	v_sqrt_f32_e32 v242, v242
	v_sqrt_f32_e32 v243, v243
	v_sqrt_f32_e32 v244, v244
	v_sqrt_f32_e32 v245, v245
	v_mul_f32_e32 v234, v242, v234
	v_mul_f32_e32 v235, v243, v235
	v_mul_f32_e32 v236, v244, v236
	v_mul_f32_e32 v237, v245, v237
	v_mul_f32_e32 v129, v129, v238
	v_add_f32_e32 v128, v128, v230
	v_add_f32_e32 v129, v129, v234
	v_mul_f32_e32 v129, v129, v239
	v_add_f32_e32 v128, v128, v231
	v_add_f32_e32 v129, v129, v235
	v_mul_f32_e32 v129, v129, v240
	v_add_f32_e32 v128, v128, v232
	v_add_f32_e32 v129, v129, v236
	v_mul_f32_e32 v129, v129, v241
	v_add_f32_e32 v128, v128, v233
	v_add_f32_e32 v129, v129, v237
	s_cmp_lt_u32 s34, 64
	s_cbranch_scc1 .Lgscan_q1
	s_waitcnt lgkmcnt(0)
	v_mul_f32_e32 v128, 0x3fb8aa3b, v128
	v_exp_f32_e32 v128, v128
	v_ashrrev_i32_e32 v139, 31, v138
	v_mov_b32_e32 v137, v164
	v_lshl_add_u64 v[130:131], v[136:137], 0, v[138:139]
	v_lshl_add_u64 v[130:131], v[130:131], 2, s[14:15]
	global_store_dword v[130:131], v128, off offset:256
	v_or3_b32 v130, v136, v141, 64
	v_ashrrev_i32_e32 v131, 31, v130
	v_lshl_add_u64 v[130:131], v[130:131], 2, s[14:15]
	global_store_dword v[130:131], v129, off
